# attention softmax row max: lane^16 / lane^32 exchange via v_permlane16_swap / v_permlane32_swap on register copies instead of two ds_bpermute round trips per tile
# speedup vs baseline: 1.0173x; 1.0132x over previous
; DEVI unsigned pk_bf16(float lo, float hi) { unsigned r; asm("v_cvt_pk_bf16_f32 %0, %1, %2" : "=v"(r) : "v"(lo), "v"(hi)); return r; }
; DEVI bf16x8 mk8(uint2 a, uint2 b) { union { uint4 u; bf16x8 v; } c; c.u = make_uint4(a.x, a.y, b.x, b.y); return c.v; }
; template <int DK, bool BIAS> ...
;     ...
; #pragma unroll
;       for (int qi = 0; qi < 2; ++qi) {
;         float mx = -3e38f;
;         if (BIAS) {
; #pragma unroll
;           for (int kt = 0; kt < 4; ++kt) { const f32x4 nf = *(const f32x4*)(fkm + buf * 64 + 16 * kt + 4 * fq);
; #pragma unroll
;             for (int r = 0; r < 4; ++r) { const float t = fmaf(S[kt][qi][r], sc2, nf[r]); S[kt][qi][r] = t; mx = fmaxf(mx, t); } }
;         } else {
; #pragma unroll
;           for (int kt = 0; kt < 4; ++kt)
; #pragma unroll
;             for (int r = 0; r < 4; ++r) mx = fmaxf(mx, S[kt][qi][r]);
;           mx *= sc2;
;         }
;         mx = fmaxf(mx, __shfl_xor(mx, 16)); mx = fmaxf(mx, __shfl_xor(mx, 32));
;         const float mold = mrun[qi], mnew = fmaxf(mold, mx);
;         mrun[qi] = mnew;
;         float ps = 0.f;
; #pragma unroll
;         for (int kt = 0; kt < 4; ++kt)
; #pragma unroll
;           for (int r = 0; r < 4; ++r) { const float pv = BIAS ? __builtin_amdgcn_exp2f(S[kt][qi][r] - mnew) : __builtin_amdgcn_exp2f(fmaf(S[kt][qi][r], sc2, -mnew)); S[kt][qi][r] = pv; ps += pv; }
;         {
;           const float alpha = __builtin_amdgcn_exp2f(mold - mnew);
;           lrun[qi] *= alpha;
; #pragma unroll
;           for (int et = 0; et < 4; ++et) O[et][qi] *= alpha;
;         }
;         lrun[qi] += ps;
; #pragma unroll
;         for (int k2 = 0; k2 < 2; ++k2) { uint2 lo, hi; lo.x = pk_bf16(S[2 * k2][qi][0], S[2 * k2][qi][1]); lo.y = pk_bf16(S[2 * k2][qi][2], S[2 * k2][qi][3]);
;           hi.x = pk_bf16(S[2 * k2 + 1][qi][0], S[2 * k2 + 1][qi][1]); hi.y = pk_bf16(S[2 * k2 + 1][qi][2], S[2 * k2 + 1][qi][3]); pf[qi][k2] = mk8(lo, hi); }
;       }
; #pragma unroll
;       for (int k2 = 0; k2 < 2; ++k2)
; #pragma unroll
;         for (int et = 0; et < 4; ++et) {
;           const uint2 v0 = *(const uint2*)(Vtm + (buf * 64 + 16 * et + fr) * 72 + 32 * k2 + 4 * fq), v1 = *(const uint2*)(Vtm + (buf * 64 + 16 * et + fr) * 72 + 32 * k2 + 16 + 4 * fq);
;           const bf16x8 va = mk8(v0, v1);
.LBB0_1776:
	s_or_b64 exec, exec, s[18:19]
	ds_read_b128 v[174:177], v168 offset:36864
	ds_read_b128 v[194:197], v168 offset:36928
	ds_read_b128 v[242:245], v168 offset:36992
	ds_read_b128 v[246:249], v168 offset:37056
	s_mov_b32 s100, 0x3e38aa3b
	s_mov_b32 s101, 0x3e38aa3b
	v_lshlrev_b32_e32 v250, 2, v186
	s_waitcnt lgkmcnt(3)
	v_pk_fma_f32 v[210:211], v[80:81], s[100:101], v[174:175]
	v_pk_fma_f32 v[212:213], v[82:83], s[100:101], v[176:177]
	v_pk_fma_f32 v[226:227], v[64:65], s[100:101], v[174:175]
	v_pk_fma_f32 v[228:229], v[66:67], s[100:101], v[176:177]
	s_waitcnt lgkmcnt(2)
	v_pk_fma_f32 v[214:215], v[86:87], s[100:101], v[194:195]
	v_pk_fma_f32 v[216:217], v[88:89], s[100:101], v[196:197]
	v_pk_fma_f32 v[230:231], v[68:69], s[100:101], v[194:195]
	v_pk_fma_f32 v[232:233], v[70:71], s[100:101], v[196:197]
	s_waitcnt lgkmcnt(1)
	v_pk_fma_f32 v[218:219], v[90:91], s[100:101], v[242:243]
	v_pk_fma_f32 v[220:221], v[92:93], s[100:101], v[244:245]
	v_pk_fma_f32 v[234:235], v[72:73], s[100:101], v[242:243]
	v_pk_fma_f32 v[236:237], v[74:75], s[100:101], v[244:245]
	s_waitcnt lgkmcnt(0)
	v_pk_fma_f32 v[222:223], v[94:95], s[100:101], v[246:247]
	v_pk_fma_f32 v[224:225], v[96:97], s[100:101], v[248:249]
	v_pk_fma_f32 v[238:239], v[76:77], s[100:101], v[246:247]
	v_pk_fma_f32 v[240:241], v[78:79], s[100:101], v[248:249]
	v_max3_f32 v84, v210, s31, v211
	v_max3_f32 v85, v226, s31, v227
	v_max3_f32 v84, v84, v212, v213
	v_max3_f32 v85, v85, v228, v229
	v_max3_f32 v84, v84, v214, v215
	v_max3_f32 v85, v85, v230, v231
	v_max3_f32 v84, v84, v216, v217
	v_max3_f32 v85, v85, v232, v233
	v_max3_f32 v84, v84, v218, v219
	v_max3_f32 v85, v85, v234, v235
	v_max3_f32 v84, v84, v220, v221
	v_max3_f32 v85, v85, v236, v237
	v_max3_f32 v84, v84, v222, v223
	v_max3_f32 v85, v85, v238, v239
	v_max3_f32 v84, v84, v224, v225
	v_max3_f32 v85, v85, v240, v241
	v_mov_b32_e32 v86, v84
	v_mov_b32_e32 v87, v85
	s_nop 1
	v_permlane16_swap_b32_e32 v86, v84
	v_permlane16_swap_b32_e32 v87, v85
	v_max_f32_e32 v84, v84, v86
	v_max_f32_e32 v85, v85, v87
	v_mov_b32_e32 v86, v84
	v_mov_b32_e32 v87, v85
	s_nop 1
	v_permlane32_swap_b32_e32 v86, v84
	v_permlane32_swap_b32_e32 v87, v85
	v_max3_f32 v131, v114, v84, v86
	v_max3_f32 v173, v112, v85, v87
	v_sub_f32_e32 v84, v114, v131
	v_sub_f32_e32 v85, v112, v173
	v_exp_f32_e32 v126, v84
	v_exp_f32_e32 v82, v85
	v_sub_f32_e32 v86, 0, v131
	v_sub_f32_e32 v80, 0, v173
	v_pk_add_f32 v[210:211], v[210:211], v[86:87] op_sel_hi:[1,0]
	v_pk_add_f32 v[212:213], v[212:213], v[86:87] op_sel_hi:[1,0]
	v_pk_add_f32 v[226:227], v[226:227], v[80:81] op_sel_hi:[1,0]
	v_pk_add_f32 v[228:229], v[228:229], v[80:81] op_sel_hi:[1,0]
	v_pk_add_f32 v[214:215], v[214:215], v[86:87] op_sel_hi:[1,0]
	v_pk_add_f32 v[216:217], v[216:217], v[86:87] op_sel_hi:[1,0]
	v_pk_add_f32 v[230:231], v[230:231], v[80:81] op_sel_hi:[1,0]
	v_pk_add_f32 v[232:233], v[232:233], v[80:81] op_sel_hi:[1,0]
	v_pk_add_f32 v[218:219], v[218:219], v[86:87] op_sel_hi:[1,0]
	v_pk_add_f32 v[220:221], v[220:221], v[86:87] op_sel_hi:[1,0]
	v_pk_add_f32 v[234:235], v[234:235], v[80:81] op_sel_hi:[1,0]
	v_pk_add_f32 v[236:237], v[236:237], v[80:81] op_sel_hi:[1,0]
	v_pk_add_f32 v[222:223], v[222:223], v[86:87] op_sel_hi:[1,0]
	v_pk_add_f32 v[224:225], v[224:225], v[86:87] op_sel_hi:[1,0]
	v_pk_add_f32 v[238:239], v[238:239], v[80:81] op_sel_hi:[1,0]
	v_pk_add_f32 v[240:241], v[240:241], v[80:81] op_sel_hi:[1,0]
	v_exp_f32_e32 v155, v210
	v_exp_f32_e32 v154, v226
	v_exp_f32_e32 v157, v211
	v_exp_f32_e32 v156, v227
	v_exp_f32_e32 v151, v212
	v_exp_f32_e32 v150, v228
	v_exp_f32_e32 v153, v213
	v_exp_f32_e32 v152, v229
	v_exp_f32_e32 v117, v214
	v_exp_f32_e32 v116, v230
	v_exp_f32_e32 v119, v215
	v_exp_f32_e32 v118, v231
	v_exp_f32_e32 v123, v216
	v_exp_f32_e32 v122, v232
	v_exp_f32_e32 v121, v217
	v_exp_f32_e32 v120, v233
	v_exp_f32_e32 v125, v218
	v_exp_f32_e32 v124, v234
	v_exp_f32_e32 v89, v219
	v_exp_f32_e32 v88, v235
	v_exp_f32_e32 v95, v220
	v_exp_f32_e32 v94, v236
	v_exp_f32_e32 v115, v221
	v_exp_f32_e32 v114, v237
	v_exp_f32_e32 v93, v222
	v_exp_f32_e32 v92, v238
	v_exp_f32_e32 v113, v223
	v_exp_f32_e32 v112, v239
	v_exp_f32_e32 v91, v224
	v_exp_f32_e32 v90, v240
	v_exp_f32_e32 v97, v225
	v_exp_f32_e32 v96, v241
	v_add_u32_e32 v242, 0x4800, v170
	v_add_u32_e32 v243, 0x5000, v170
	v_add_u32_e32 v244, 0x5800, v170
	v_add_u32_e32 v245, 0x6000, v170
	ds_read2_b64 v[210:213], v242 offset1:4
	ds_read2_b64 v[214:217], v243 offset0:32 offset1:36
	ds_read2_b64 v[218:221], v244 offset0:64 offset1:68
	ds_read2_b64 v[222:225], v245 offset0:96 offset1:100
	ds_read2_b64 v[226:229], v242 offset0:8 offset1:12
	ds_read2_b64 v[230:233], v243 offset0:40 offset1:44
	ds_read2_b64 v[234:237], v244 offset0:72 offset1:76
	ds_read2_b64 v[238:241], v245 offset0:104 offset1:108
	v_pk_mul_f32 v[202:203], v[52:53], v[126:127] op_sel_hi:[1,0]
	v_pk_mul_f32 v[52:53], v[56:57], v[126:127] op_sel_hi:[1,0]
	v_pk_mul_f32 v[198:199], v[48:49], v[126:127] op_sel_hi:[1,0]
	v_pk_mul_f32 v[48:49], v[60:61], v[126:127] op_sel_hi:[1,0]
	v_pk_mul_f32 v[200:201], v[50:51], v[126:127] op_sel_hi:[1,0]
	v_pk_mul_f32 v[204:205], v[54:55], v[126:127] op_sel_hi:[1,0]
	v_pk_add_f32 v[64:65], v[154:155], 0 op_sel_hi:[1,0]
	v_pk_add_f32 v[80:81], v[156:157], v[64:65]
	v_pk_mul_f32 v[46:47], v[46:47], v[82:83] op_sel_hi:[1,0]
	v_pk_mul_f32 v[44:45], v[44:45], v[82:83] op_sel_hi:[1,0]
	v_pk_mul_f32 v[54:55], v[58:59], v[126:127] op_sel_hi:[1,0]
	v_cvt_pk_bf16_f32 v56, v155, v157
	v_cvt_pk_bf16_f32 v57, v151, v153
	v_cvt_pk_bf16_f32 v58, v117, v119
	v_cvt_pk_bf16_f32 v59, v123, v121
	v_cvt_pk_bf16_f32 v68, v154, v156
	s_waitcnt lgkmcnt(7)
; DEVI unsigned pk_bf16(float lo, float hi) { unsigned r; asm("v_cvt_pk_bf16_f32 %0, %1, %2" : "=v"(r) : "v"(lo), "v"(hi)); return r; }
; DEVI bf16x8 mk8(uint2 a, uint2 b) { union { uint4 u; bf16x8 v; } c; c.u = make_uint4(a.x, a.y, b.x, b.y); return c.v; }
; #define MFMA(a, b, c) __builtin_amdgcn_mfma_f32_16x16x32_bf16((a), (b), (c), 0, 0, 0)
; template <int DK, bool BIAS> ...
;     ...
;         float ps = 0.f;
; #pragma unroll
;         for (int kt = 0; kt < 4; ++kt)
; #pragma unroll
;           for (int r = 0; r < 4; ++r) { const float pv = BIAS ? __builtin_amdgcn_exp2f(S[kt][qi][r] - mnew) : __builtin_amdgcn_exp2f(fmaf(S[kt][qi][r], sc2, -mnew)); S[kt][qi][r] = pv; ps += pv; }
;         {
;           const float alpha = __builtin_amdgcn_exp2f(mold - mnew);
;           lrun[qi] *= alpha;
; #pragma unroll
;           for (int et = 0; et < 4; ++et) O[et][qi] *= alpha;
;         }
;         lrun[qi] += ps;
; #pragma unroll
;         for (int k2 = 0; k2 < 2; ++k2) { uint2 lo, hi; lo.x = pk_bf16(S[2 * k2][qi][0], S[2 * k2][qi][1]); lo.y = pk_bf16(S[2 * k2][qi][2], S[2 * k2][qi][3]);
;           hi.x = pk_bf16(S[2 * k2 + 1][qi][0], S[2 * k2 + 1][qi][1]); hi.y = pk_bf16(S[2 * k2 + 1][qi][2], S[2 * k2 + 1][qi][3]); pf[qi][k2] = mk8(lo, hi); }
;       }
; #pragma unroll
;       for (int k2 = 0; k2 < 2; ++k2)
; #pragma unroll
;         for (int et = 0; et < 4; ++et) {
;           const uint2 v0 = *(const uint2*)(Vtm + (buf * 64 + 16 * et + fr) * 72 + 32 * k2 + 4 * fq), v1 = *(const uint2*)(Vtm + (buf * 64 + 16 * et + fr) * 72 + 32 * k2 + 16 + 4 * fq);
;           const bf16x8 va = mk8(v0, v1);
; #pragma unroll
;           for (int qi = 0; qi < 2; ++qi) O[et][qi] = MFMA(va, pf[qi][k2], O[et][qi]);
;         }
	v_mfma_f32_16x16x32_bf16 v[76:79], v[210:213], v[56:59], v[198:201]
	v_cvt_pk_bf16_f32 v69, v150, v152
	v_cvt_pk_bf16_f32 v70, v116, v118
	v_cvt_pk_bf16_f32 v71, v122, v120
	v_pk_mul_f32 v[42:43], v[42:43], v[82:83] op_sel_hi:[1,0]
	s_nop 0
	v_mfma_f32_16x16x32_bf16 v[44:47], v[210:213], v[68:71], v[44:47]
	v_pk_mul_f32 v[40:41], v[40:41], v[82:83] op_sel_hi:[1,0]
	s_waitcnt lgkmcnt(6)
	v_mfma_f32_16x16x32_bf16 v[84:87], v[214:217], v[56:59], v[202:205]
	v_pk_mul_f32 v[50:51], v[62:63], v[126:127] op_sel_hi:[1,0]
	v_mfma_f32_16x16x32_bf16 v[40:43], v[214:217], v[68:71], v[40:43]
	v_pk_mul_f32 v[38:39], v[38:39], v[82:83] op_sel_hi:[1,0]
	v_pk_mul_f32 v[36:37], v[36:37], v[82:83] op_sel_hi:[1,0]
	s_waitcnt lgkmcnt(5)
	v_mfma_f32_16x16x32_bf16 v[154:157], v[218:221], v[56:59], v[52:55]
	v_pk_mul_f32 v[34:35], v[34:35], v[82:83] op_sel_hi:[1,0]
	v_pk_mul_f32 v[32:33], v[32:33], v[82:83] op_sel_hi:[1,0]
	v_cvt_pk_bf16_f32 v60, v125, v89
	v_mfma_f32_16x16x32_bf16 v[36:39], v[218:221], v[68:71], v[36:39]
	s_waitcnt lgkmcnt(4)
	v_mfma_f32_16x16x32_bf16 v[64:67], v[222:225], v[56:59], v[48:51]
	v_cvt_pk_bf16_f32 v61, v95, v115
	v_cvt_pk_bf16_f32 v62, v93, v113
	v_cvt_pk_bf16_f32 v63, v91, v97
	s_nop 0
	v_mfma_f32_16x16x32_bf16 v[32:35], v[222:225], v[68:71], v[32:35]
	v_cvt_pk_bf16_f32 v68, v124, v88
	v_cvt_pk_bf16_f32 v69, v94, v114
	s_waitcnt lgkmcnt(3)
	v_mfma_f32_16x16x32_bf16 v[48:51], v[226:229], v[60:63], v[76:79]
	v_cvt_pk_bf16_f32 v70, v92, v112
	v_cvt_pk_bf16_f32 v71, v90, v96
	s_nop 1
	v_mfma_f32_16x16x32_bf16 v[44:47], v[226:229], v[68:71], v[44:47]
	v_pk_add_f32 v[52:53], v[150:151], v[80:81]
	v_mov_b32_e32 v83, v126
	v_pk_add_f32 v[76:77], v[152:153], v[52:53]
	s_waitcnt lgkmcnt(2)
	v_mfma_f32_16x16x32_bf16 v[52:55], v[230:233], v[60:63], v[84:87]
	v_pk_add_f32 v[76:77], v[116:117], v[76:77]
	v_pk_add_f32 v[76:77], v[118:119], v[76:77]
	v_mfma_f32_16x16x32_bf16 v[40:43], v[230:233], v[68:71], v[40:43]
	v_pk_add_f32 v[76:77], v[122:123], v[76:77]
	v_pk_add_f32 v[56:57], v[120:121], v[76:77]
	v_pk_add_f32 v[80:81], v[124:125], v[56:57]
	s_waitcnt lgkmcnt(1)
	v_mfma_f32_16x16x32_bf16 v[56:59], v[234:237], v[60:63], v[154:157]
	v_pk_add_f32 v[80:81], v[88:89], v[80:81]
	v_pk_add_f32 v[80:81], v[94:95], v[80:81]
	v_mfma_f32_16x16x32_bf16 v[36:39], v[234:237], v[68:71], v[36:39]
	v_pk_add_f32 v[80:81], v[114:115], v[80:81]
	v_mov_b32_e32 v114, v131
	v_pk_add_f32 v[72:73], v[92:93], v[80:81]
	s_waitcnt lgkmcnt(0)
	v_mfma_f32_16x16x32_bf16 v[60:63], v[238:241], v[60:63], v[64:67]
	v_pk_add_f32 v[72:73], v[112:113], v[72:73]
	v_mov_b32_e32 v112, v173
	v_mfma_f32_16x16x32_bf16 v[32:35], v[238:241], v[68:71], v[32:35]
	v_pk_add_f32 v[64:65], v[90:91], v[72:73]
	v_pk_add_f32 v[64:65], v[96:97], v[64:65]
	s_nop 0
	v_pk_fma_f32 v[106:107], v[106:107], v[82:83], v[64:65]

; DEVI unsigned pk_bf16(float lo, float hi) { unsigned r; asm("v_cvt_pk_bf16_f32 %0, %1, %2" : "=v"(r) : "v"(lo), "v"(hi)); return r; }
; DEVI bf16x8 mk8(uint2 a, uint2 b) { union { uint4 u; bf16x8 v; } c; c.u = make_uint4(a.x, a.y, b.x, b.y); return c.v; }
; template <int DK, bool BIAS> ...
;     ...
; #pragma unroll
;       for (int qi = 0; qi < 2; ++qi) {
;         float mx = -3e38f;
;         if (BIAS) {
; #pragma unroll
;           for (int kt = 0; kt < 4; ++kt) { const f32x4 nf = *(const f32x4*)(fkm + buf * 64 + 16 * kt + 4 * fq);
; #pragma unroll
;             for (int r = 0; r < 4; ++r) { const float t = fmaf(S[kt][qi][r], sc2, nf[r]); S[kt][qi][r] = t; mx = fmaxf(mx, t); } }
;         } else {
; #pragma unroll
;           for (int kt = 0; kt < 4; ++kt)
; #pragma unroll
;             for (int r = 0; r < 4; ++r) mx = fmaxf(mx, S[kt][qi][r]);
;           mx *= sc2;
;         }
;         mx = fmaxf(mx, __shfl_xor(mx, 16)); mx = fmaxf(mx, __shfl_xor(mx, 32));
;         const float mold = mrun[qi], mnew = fmaxf(mold, mx);
;         mrun[qi] = mnew;
;         float ps = 0.f;
; #pragma unroll
;         for (int kt = 0; kt < 4; ++kt)
; #pragma unroll
;           for (int r = 0; r < 4; ++r) { const float pv = BIAS ? __builtin_amdgcn_exp2f(S[kt][qi][r] - mnew) : __builtin_amdgcn_exp2f(fmaf(S[kt][qi][r], sc2, -mnew)); S[kt][qi][r] = pv; ps += pv; }
;         {
;           const float alpha = __builtin_amdgcn_exp2f(mold - mnew);
;           lrun[qi] *= alpha;
; #pragma unroll
;           for (int et = 0; et < 4; ++et) O[et][qi] *= alpha;
;         }
;         lrun[qi] += ps;
; #pragma unroll
;         for (int k2 = 0; k2 < 2; ++k2) { uint2 lo, hi; lo.x = pk_bf16(S[2 * k2][qi][0], S[2 * k2][qi][1]); lo.y = pk_bf16(S[2 * k2][qi][2], S[2 * k2][qi][3]);
;           hi.x = pk_bf16(S[2 * k2 + 1][qi][0], S[2 * k2 + 1][qi][1]); hi.y = pk_bf16(S[2 * k2 + 1][qi][2], S[2 * k2 + 1][qi][3]); pf[qi][k2] = mk8(lo, hi); }
;       }
; #pragma unroll
;       for (int k2 = 0; k2 < 2; ++k2)
; #pragma unroll
;         for (int et = 0; et < 4; ++et) {
;           const uint2 v0 = *(const uint2*)(Vtm + (buf * 64 + 16 * et + fr) * 72 + 32 * k2 + 4 * fq), v1 = *(const uint2*)(Vtm + (buf * 64 + 16 * et + fr) * 72 + 32 * k2 + 16 + 4 * fq);
;           const bf16x8 va = mk8(v0, v1);
.LBB0_1797:
	s_or_b64 exec, exec, s[18:19]
	ds_read_b128 v[174:177], v104 offset:37120
	ds_read_b128 v[194:197], v104 offset:37184
	ds_read_b128 v[242:245], v104 offset:37248
	ds_read_b128 v[246:249], v104 offset:37312
	s_mov_b32 s100, 0x3e38aa3b
	s_mov_b32 s101, 0x3e38aa3b
	v_lshlrev_b32_e32 v250, 2, v186
	s_waitcnt lgkmcnt(3)
	v_pk_fma_f32 v[210:211], v[80:81], s[100:101], v[174:175]
	v_pk_fma_f32 v[212:213], v[82:83], s[100:101], v[176:177]
	v_pk_fma_f32 v[226:227], v[64:65], s[100:101], v[174:175]
	v_pk_fma_f32 v[228:229], v[66:67], s[100:101], v[176:177]
	s_waitcnt lgkmcnt(2)
	v_pk_fma_f32 v[214:215], v[86:87], s[100:101], v[194:195]
	v_pk_fma_f32 v[216:217], v[88:89], s[100:101], v[196:197]
	v_pk_fma_f32 v[230:231], v[68:69], s[100:101], v[194:195]
	v_pk_fma_f32 v[232:233], v[70:71], s[100:101], v[196:197]
	s_waitcnt lgkmcnt(1)
	v_pk_fma_f32 v[218:219], v[90:91], s[100:101], v[242:243]
	v_pk_fma_f32 v[220:221], v[92:93], s[100:101], v[244:245]
	v_pk_fma_f32 v[234:235], v[72:73], s[100:101], v[242:243]
	v_pk_fma_f32 v[236:237], v[74:75], s[100:101], v[244:245]
	s_waitcnt lgkmcnt(0)
	v_pk_fma_f32 v[222:223], v[94:95], s[100:101], v[246:247]
	v_pk_fma_f32 v[224:225], v[96:97], s[100:101], v[248:249]
	v_pk_fma_f32 v[238:239], v[76:77], s[100:101], v[246:247]
	v_pk_fma_f32 v[240:241], v[78:79], s[100:101], v[248:249]
	v_max3_f32 v84, v210, s31, v211
	v_max3_f32 v85, v226, s31, v227
	v_max3_f32 v84, v84, v212, v213
	v_max3_f32 v85, v85, v228, v229
	v_max3_f32 v84, v84, v214, v215
	v_max3_f32 v85, v85, v230, v231
	v_max3_f32 v84, v84, v216, v217
	v_max3_f32 v85, v85, v232, v233
	v_max3_f32 v84, v84, v218, v219
	v_max3_f32 v85, v85, v234, v235
	v_max3_f32 v84, v84, v220, v221
	v_max3_f32 v85, v85, v236, v237
	v_max3_f32 v84, v84, v222, v223
	v_max3_f32 v85, v85, v238, v239
	v_max3_f32 v84, v84, v224, v225
	v_max3_f32 v85, v85, v240, v241
	v_mov_b32_e32 v86, v84
	v_mov_b32_e32 v87, v85
	s_nop 1
	v_permlane16_swap_b32_e32 v86, v84
	v_permlane16_swap_b32_e32 v87, v85
	v_max_f32_e32 v84, v84, v86
	v_max_f32_e32 v85, v85, v87
	v_mov_b32_e32 v86, v84
	v_mov_b32_e32 v87, v85
	s_nop 1
	v_permlane32_swap_b32_e32 v86, v84
	v_permlane32_swap_b32_e32 v87, v85
	v_max3_f32 v131, v114, v84, v86
	v_max3_f32 v173, v112, v85, v87
	v_sub_f32_e32 v84, v114, v131
	v_sub_f32_e32 v85, v112, v173
	v_exp_f32_e32 v126, v84
	v_exp_f32_e32 v82, v85
	v_sub_f32_e32 v86, 0, v131
	v_sub_f32_e32 v80, 0, v173
	v_pk_add_f32 v[210:211], v[210:211], v[86:87] op_sel_hi:[1,0]
	v_pk_add_f32 v[212:213], v[212:213], v[86:87] op_sel_hi:[1,0]
	v_pk_add_f32 v[226:227], v[226:227], v[80:81] op_sel_hi:[1,0]
	v_pk_add_f32 v[228:229], v[228:229], v[80:81] op_sel_hi:[1,0]
	v_pk_add_f32 v[214:215], v[214:215], v[86:87] op_sel_hi:[1,0]
	v_pk_add_f32 v[216:217], v[216:217], v[86:87] op_sel_hi:[1,0]
	v_pk_add_f32 v[230:231], v[230:231], v[80:81] op_sel_hi:[1,0]
	v_pk_add_f32 v[232:233], v[232:233], v[80:81] op_sel_hi:[1,0]
	v_pk_add_f32 v[218:219], v[218:219], v[86:87] op_sel_hi:[1,0]
	v_pk_add_f32 v[220:221], v[220:221], v[86:87] op_sel_hi:[1,0]
	v_pk_add_f32 v[234:235], v[234:235], v[80:81] op_sel_hi:[1,0]
	v_pk_add_f32 v[236:237], v[236:237], v[80:81] op_sel_hi:[1,0]
	v_pk_add_f32 v[222:223], v[222:223], v[86:87] op_sel_hi:[1,0]
	v_pk_add_f32 v[224:225], v[224:225], v[86:87] op_sel_hi:[1,0]
	v_pk_add_f32 v[238:239], v[238:239], v[80:81] op_sel_hi:[1,0]
	v_pk_add_f32 v[240:241], v[240:241], v[80:81] op_sel_hi:[1,0]
	v_exp_f32_e32 v155, v210
	v_exp_f32_e32 v154, v226
	v_exp_f32_e32 v157, v211
	v_exp_f32_e32 v156, v227
	v_exp_f32_e32 v151, v212
	v_exp_f32_e32 v150, v228
	v_exp_f32_e32 v153, v213
	v_exp_f32_e32 v152, v229
	v_exp_f32_e32 v117, v214
	v_exp_f32_e32 v116, v230
	v_exp_f32_e32 v119, v215
	v_exp_f32_e32 v118, v231
	v_exp_f32_e32 v123, v216
	v_exp_f32_e32 v122, v232
	v_exp_f32_e32 v121, v217
	v_exp_f32_e32 v120, v233
	v_exp_f32_e32 v125, v218
	v_exp_f32_e32 v124, v234
	v_exp_f32_e32 v89, v219
	v_exp_f32_e32 v88, v235
	v_exp_f32_e32 v95, v220
	v_exp_f32_e32 v94, v236
	v_exp_f32_e32 v115, v221
	v_exp_f32_e32 v114, v237
	v_exp_f32_e32 v93, v222
	v_exp_f32_e32 v92, v238
	v_exp_f32_e32 v113, v223
	v_exp_f32_e32 v112, v239
	v_exp_f32_e32 v91, v224
	v_exp_f32_e32 v90, v240
	v_exp_f32_e32 v97, v225
	v_exp_f32_e32 v96, v241
	v_add_u32_e32 v242, 0x6800, v170
	v_add_u32_e32 v243, 0x7000, v170
	v_add_u32_e32 v244, 0x7800, v170
	v_add_u32_e32 v245, 0x8000, v170
	ds_read2_b64 v[210:213], v242 offset0:128 offset1:132
	ds_read2_b64 v[214:217], v243 offset0:160 offset1:164
	ds_read2_b64 v[218:221], v244 offset0:192 offset1:196
	ds_read2_b64 v[222:225], v245 offset0:224 offset1:228
	ds_read2_b64 v[226:229], v242 offset0:136 offset1:140
	ds_read2_b64 v[230:233], v243 offset0:168 offset1:172
	ds_read2_b64 v[234:237], v244 offset0:200 offset1:204
	ds_read2_b64 v[238:241], v245 offset0:232 offset1:236
	v_pk_mul_f32 v[202:203], v[52:53], v[126:127] op_sel_hi:[1,0]
	v_pk_mul_f32 v[52:53], v[56:57], v[126:127] op_sel_hi:[1,0]
	v_pk_mul_f32 v[198:199], v[48:49], v[126:127] op_sel_hi:[1,0]
	v_pk_mul_f32 v[48:49], v[60:61], v[126:127] op_sel_hi:[1,0]
	v_pk_mul_f32 v[200:201], v[50:51], v[126:127] op_sel_hi:[1,0]
	v_pk_mul_f32 v[204:205], v[54:55], v[126:127] op_sel_hi:[1,0]
	v_pk_add_f32 v[64:65], v[154:155], 0 op_sel_hi:[1,0]
	v_pk_add_f32 v[80:81], v[156:157], v[64:65]
	v_pk_mul_f32 v[46:47], v[46:47], v[82:83] op_sel_hi:[1,0]
	v_pk_mul_f32 v[44:45], v[44:45], v[82:83] op_sel_hi:[1,0]
	v_pk_mul_f32 v[54:55], v[58:59], v[126:127] op_sel_hi:[1,0]
	v_cvt_pk_bf16_f32 v56, v155, v157
	v_cvt_pk_bf16_f32 v57, v151, v153
	v_cvt_pk_bf16_f32 v58, v117, v119
	v_cvt_pk_bf16_f32 v59, v123, v121
	v_cvt_pk_bf16_f32 v68, v154, v156
	s_waitcnt lgkmcnt(7)
; DEVI unsigned pk_bf16(float lo, float hi) { unsigned r; asm("v_cvt_pk_bf16_f32 %0, %1, %2" : "=v"(r) : "v"(lo), "v"(hi)); return r; }
; DEVI bf16x8 mk8(uint2 a, uint2 b) { union { uint4 u; bf16x8 v; } c; c.u = make_uint4(a.x, a.y, b.x, b.y); return c.v; }
; #define MFMA(a, b, c) __builtin_amdgcn_mfma_f32_16x16x32_bf16((a), (b), (c), 0, 0, 0)
; template <int DK, bool BIAS> ...
;     ...
;         float ps = 0.f;
; #pragma unroll
;         for (int kt = 0; kt < 4; ++kt)
; #pragma unroll
;           for (int r = 0; r < 4; ++r) { const float pv = BIAS ? __builtin_amdgcn_exp2f(S[kt][qi][r] - mnew) : __builtin_amdgcn_exp2f(fmaf(S[kt][qi][r], sc2, -mnew)); S[kt][qi][r] = pv; ps += pv; }
;         {
;           const float alpha = __builtin_amdgcn_exp2f(mold - mnew);
;           lrun[qi] *= alpha;
; #pragma unroll
;           for (int et = 0; et < 4; ++et) O[et][qi] *= alpha;
;         }
;         lrun[qi] += ps;
; #pragma unroll
;         for (int k2 = 0; k2 < 2; ++k2) { uint2 lo, hi; lo.x = pk_bf16(S[2 * k2][qi][0], S[2 * k2][qi][1]); lo.y = pk_bf16(S[2 * k2][qi][2], S[2 * k2][qi][3]);
;           hi.x = pk_bf16(S[2 * k2 + 1][qi][0], S[2 * k2 + 1][qi][1]); hi.y = pk_bf16(S[2 * k2 + 1][qi][2], S[2 * k2 + 1][qi][3]); pf[qi][k2] = mk8(lo, hi); }
;       }
; #pragma unroll
;       for (int k2 = 0; k2 < 2; ++k2)
; #pragma unroll
;         for (int et = 0; et < 4; ++et) {
;           const uint2 v0 = *(const uint2*)(Vtm + (buf * 64 + 16 * et + fr) * 72 + 32 * k2 + 4 * fq), v1 = *(const uint2*)(Vtm + (buf * 64 + 16 * et + fr) * 72 + 32 * k2 + 16 + 4 * fq);
;           const bf16x8 va = mk8(v0, v1);
; #pragma unroll
;           for (int qi = 0; qi < 2; ++qi) O[et][qi] = MFMA(va, pf[qi][k2], O[et][qi]);
;         }
	v_mfma_f32_16x16x32_bf16 v[76:79], v[210:213], v[56:59], v[198:201]
	v_cvt_pk_bf16_f32 v69, v150, v152
	v_cvt_pk_bf16_f32 v70, v116, v118
	v_cvt_pk_bf16_f32 v71, v122, v120
	v_pk_mul_f32 v[42:43], v[42:43], v[82:83] op_sel_hi:[1,0]
	s_nop 0
	v_mfma_f32_16x16x32_bf16 v[44:47], v[210:213], v[68:71], v[44:47]
	v_pk_mul_f32 v[40:41], v[40:41], v[82:83] op_sel_hi:[1,0]
	s_waitcnt lgkmcnt(6)
	v_mfma_f32_16x16x32_bf16 v[84:87], v[214:217], v[56:59], v[202:205]
	v_pk_mul_f32 v[50:51], v[62:63], v[126:127] op_sel_hi:[1,0]
	v_mfma_f32_16x16x32_bf16 v[40:43], v[214:217], v[68:71], v[40:43]
	v_pk_mul_f32 v[38:39], v[38:39], v[82:83] op_sel_hi:[1,0]
	v_pk_mul_f32 v[36:37], v[36:37], v[82:83] op_sel_hi:[1,0]
	s_waitcnt lgkmcnt(5)
	v_mfma_f32_16x16x32_bf16 v[154:157], v[218:221], v[56:59], v[52:55]
	v_pk_mul_f32 v[34:35], v[34:35], v[82:83] op_sel_hi:[1,0]
	v_pk_mul_f32 v[32:33], v[32:33], v[82:83] op_sel_hi:[1,0]
	v_cvt_pk_bf16_f32 v60, v125, v89
	v_mfma_f32_16x16x32_bf16 v[36:39], v[218:221], v[68:71], v[36:39]
	s_waitcnt lgkmcnt(4)
	v_mfma_f32_16x16x32_bf16 v[64:67], v[222:225], v[56:59], v[48:51]
	v_cvt_pk_bf16_f32 v61, v95, v115
	v_cvt_pk_bf16_f32 v62, v93, v113
	v_cvt_pk_bf16_f32 v63, v91, v97
	s_nop 0
	v_mfma_f32_16x16x32_bf16 v[32:35], v[222:225], v[68:71], v[32:35]
	v_cvt_pk_bf16_f32 v68, v124, v88
	v_cvt_pk_bf16_f32 v69, v94, v114
	s_waitcnt lgkmcnt(3)
	v_mfma_f32_16x16x32_bf16 v[48:51], v[226:229], v[60:63], v[76:79]
	v_cvt_pk_bf16_f32 v70, v92, v112
	v_cvt_pk_bf16_f32 v71, v90, v96
	s_nop 1
	v_mfma_f32_16x16x32_bf16 v[44:47], v[226:229], v[68:71], v[44:47]
	v_pk_add_f32 v[52:53], v[150:151], v[80:81]
	v_mov_b32_e32 v83, v126
	v_pk_add_f32 v[76:77], v[152:153], v[52:53]
	s_waitcnt lgkmcnt(2)
	v_mfma_f32_16x16x32_bf16 v[52:55], v[230:233], v[60:63], v[84:87]
	v_pk_add_f32 v[76:77], v[116:117], v[76:77]
	v_pk_add_f32 v[76:77], v[118:119], v[76:77]
	v_mfma_f32_16x16x32_bf16 v[40:43], v[230:233], v[68:71], v[40:43]
	v_pk_add_f32 v[76:77], v[122:123], v[76:77]
	v_pk_add_f32 v[56:57], v[120:121], v[76:77]
	v_pk_add_f32 v[80:81], v[124:125], v[56:57]
	s_waitcnt lgkmcnt(1)
	v_mfma_f32_16x16x32_bf16 v[56:59], v[234:237], v[60:63], v[154:157]
	v_pk_add_f32 v[80:81], v[88:89], v[80:81]
	v_pk_add_f32 v[80:81], v[94:95], v[80:81]
	v_mfma_f32_16x16x32_bf16 v[36:39], v[234:237], v[68:71], v[36:39]
	v_pk_add_f32 v[80:81], v[114:115], v[80:81]
	v_mov_b32_e32 v114, v131
	v_pk_add_f32 v[72:73], v[92:93], v[80:81]
	s_waitcnt lgkmcnt(0)
	v_mfma_f32_16x16x32_bf16 v[60:63], v[238:241], v[60:63], v[64:67]
	v_pk_add_f32 v[72:73], v[112:113], v[72:73]
	v_mov_b32_e32 v112, v173
	v_mfma_f32_16x16x32_bf16 v[32:35], v[238:241], v[68:71], v[32:35]
	v_pk_add_f32 v[64:65], v[90:91], v[72:73]
	v_pk_add_f32 v[64:65], v[96:97], v[64:65]
	s_nop 0
	v_pk_fma_f32 v[106:107], v[106:107], v[82:83], v[64:65]

; DEVI unsigned pk_bf16(float lo, float hi) { unsigned r; asm("v_cvt_pk_bf16_f32 %0, %1, %2" : "=v"(r) : "v"(lo), "v"(hi)); return r; }
; DEVI bf16x8 mk8(uint2 a, uint2 b) { union { uint4 u; bf16x8 v; } c; c.u = make_uint4(a.x, a.y, b.x, b.y); return c.v; }
; template <int DK, bool BIAS> ...
;     ...
;       for (int qi = 0; qi < 2; ++qi) {
;         float mx = -3e38f;
;         if (BIAS) {
; #pragma unroll
;           for (int kt = 0; kt < 4; ++kt) { const f32x4 nf = *(const f32x4*)(fkm + buf * 64 + 16 * kt + 4 * fq);
; #pragma unroll
;             for (int r = 0; r < 4; ++r) { const float t = fmaf(S[kt][qi][r], sc2, nf[r]); S[kt][qi][r] = t; mx = fmaxf(mx, t); } }
;         } else {
; #pragma unroll
;           for (int kt = 0; kt < 4; ++kt)
; #pragma unroll
;             for (int r = 0; r < 4; ++r) mx = fmaxf(mx, S[kt][qi][r]);
;           mx *= sc2;
;         }
;         mx = fmaxf(mx, __shfl_xor(mx, 16)); mx = fmaxf(mx, __shfl_xor(mx, 32));
;         const float mold = mrun[qi], mnew = fmaxf(mold, mx);
;         mrun[qi] = mnew;
;         float ps = 0.f;
; #pragma unroll
;         for (int kt = 0; kt < 4; ++kt)
; #pragma unroll
;           for (int r = 0; r < 4; ++r) { const float pv = BIAS ? __builtin_amdgcn_exp2f(S[kt][qi][r] - mnew) : __builtin_amdgcn_exp2f(fmaf(S[kt][qi][r], sc2, -mnew)); S[kt][qi][r] = pv; ps += pv; }
;         {
;           const float alpha = __builtin_amdgcn_exp2f(mold - mnew);
;           lrun[qi] *= alpha;
; #pragma unroll
;           for (int et = 0; et < 4; ++et) O[et][qi] *= alpha;
;         }
;         lrun[qi] += ps;
; #pragma unroll
;         for (int k2 = 0; k2 < 2; ++k2) { uint2 lo, hi; lo.x = pk_bf16(S[2 * k2][qi][0], S[2 * k2][qi][1]); lo.y = pk_bf16(S[2 * k2][qi][2], S[2 * k2][qi][3]);
;           hi.x = pk_bf16(S[2 * k2 + 1][qi][0], S[2 * k2 + 1][qi][1]); hi.y = pk_bf16(S[2 * k2 + 1][qi][2], S[2 * k2 + 1][qi][3]); pf[qi][k2] = mk8(lo, hi); }
;       }
; #pragma unroll
;       for (int k2 = 0; k2 < 2; ++k2)
; #pragma unroll
;         for (int et = 0; et < 4; ++et) {
;           const uint2 v0 = *(const uint2*)(Vtm + (buf * 64 + 16 * et + fr) * 72 + 32 * k2 + 4 * fq), v1 = *(const uint2*)(Vtm + (buf * 64 + 16 * et + fr) * 72 + 32 * k2 + 16 + 4 * fq);
;           const bf16x8 va = mk8(v0, v1);
; #pragma unroll
;           for (int qi = 0; qi < 2; ++qi) O[et][qi] = MFMA(va, pf[qi][k2], O[et][qi]);
;         }
.LBB0_1866:
	s_or_b64 exec, exec, s[18:19]
	s_mov_b32 s100, s34
	s_mov_b32 s101, s34
	v_lshlrev_b32_e32 v250, 2, v186
	v_max3_f32 v242, v96, s31, v97
	v_max3_f32 v243, v84, s31, v85
	v_max3_f32 v242, v242, v98, v99
	v_max3_f32 v243, v243, v86, v87
	v_max3_f32 v242, v242, v100, v101
	v_max3_f32 v243, v243, v88, v89
	v_max3_f32 v242, v242, v102, v103
	v_max3_f32 v243, v243, v90, v91
	v_max3_f32 v242, v242, v104, v105
	v_max3_f32 v243, v243, v80, v81
	v_max3_f32 v242, v242, v106, v107
	v_max3_f32 v243, v243, v82, v83
	v_max3_f32 v242, v242, v108, v109
	v_max3_f32 v243, v243, v92, v93
	v_max3_f32 v242, v242, v110, v111
	v_max3_f32 v243, v243, v94, v95
	v_mul_f32_e32 v242, 0x3e16c740, v242
	v_mul_f32_e32 v243, 0x3e16c740, v243
	v_mov_b32_e32 v244, v242
	v_mov_b32_e32 v245, v243
	s_nop 1
	v_permlane16_swap_b32_e32 v244, v242
	v_permlane16_swap_b32_e32 v245, v243
	v_max_f32_e32 v242, v242, v244
	v_max_f32_e32 v243, v243, v245
	v_mov_b32_e32 v244, v242
	v_mov_b32_e32 v245, v243
	s_nop 1
	v_permlane32_swap_b32_e32 v244, v242
	v_permlane32_swap_b32_e32 v245, v243
	v_max3_f32 v131, v154, v242, v244
	v_max3_f32 v209, v208, v243, v245
	v_sub_f32_e32 v242, v154, v131
	v_sub_f32_e32 v243, v208, v209
	v_sub_f32_e32 v246, 0, v131
	v_sub_f32_e32 v248, 0, v209
	v_pk_fma_f32 v[210:211], v[96:97], s[100:101], v[246:247] op_sel_hi:[1,1,0]
	v_pk_fma_f32 v[226:227], v[80:81], s[100:101], v[248:249] op_sel_hi:[1,1,0]
	v_pk_fma_f32 v[212:213], v[98:99], s[100:101], v[246:247] op_sel_hi:[1,1,0]
	v_pk_fma_f32 v[228:229], v[82:83], s[100:101], v[248:249] op_sel_hi:[1,1,0]
	v_pk_fma_f32 v[214:215], v[100:101], s[100:101], v[246:247] op_sel_hi:[1,1,0]
	v_pk_fma_f32 v[230:231], v[84:85], s[100:101], v[248:249] op_sel_hi:[1,1,0]
	v_pk_fma_f32 v[216:217], v[102:103], s[100:101], v[246:247] op_sel_hi:[1,1,0]
	v_pk_fma_f32 v[232:233], v[86:87], s[100:101], v[248:249] op_sel_hi:[1,1,0]
	v_pk_fma_f32 v[218:219], v[104:105], s[100:101], v[246:247] op_sel_hi:[1,1,0]
	v_pk_fma_f32 v[234:235], v[88:89], s[100:101], v[248:249] op_sel_hi:[1,1,0]
	v_pk_fma_f32 v[220:221], v[106:107], s[100:101], v[246:247] op_sel_hi:[1,1,0]
	v_pk_fma_f32 v[236:237], v[90:91], s[100:101], v[248:249] op_sel_hi:[1,1,0]
	v_pk_fma_f32 v[222:223], v[108:109], s[100:101], v[246:247] op_sel_hi:[1,1,0]
	v_pk_fma_f32 v[238:239], v[92:93], s[100:101], v[248:249] op_sel_hi:[1,1,0]
	v_pk_fma_f32 v[224:225], v[110:111], s[100:101], v[246:247] op_sel_hi:[1,1,0]
	v_pk_fma_f32 v[240:241], v[94:95], s[100:101], v[248:249] op_sel_hi:[1,1,0]
	v_exp_f32_e32 v178, v242
	v_exp_f32_e32 v90, v243
	v_exp_f32_e32 v163, v210
	v_exp_f32_e32 v170, v226
	v_exp_f32_e32 v165, v211
	v_exp_f32_e32 v104, v227
	v_exp_f32_e32 v167, v212
	v_exp_f32_e32 v172, v228
	v_exp_f32_e32 v169, v213
	v_exp_f32_e32 v106, v229
	v_exp_f32_e32 v155, v214
	v_exp_f32_e32 v162, v230
	v_exp_f32_e32 v157, v215
	v_exp_f32_e32 v164, v231
	v_exp_f32_e32 v159, v216
	v_exp_f32_e32 v166, v232
	v_exp_f32_e32 v161, v217
	v_exp_f32_e32 v168, v233
	v_exp_f32_e32 v171, v218
	v_exp_f32_e32 v154, v234
	v_exp_f32_e32 v105, v219
	v_exp_f32_e32 v156, v235
	v_exp_f32_e32 v173, v220
	v_exp_f32_e32 v158, v236
	v_exp_f32_e32 v107, v221
	v_exp_f32_e32 v160, v237
	v_exp_f32_e32 v175, v222
	v_exp_f32_e32 v174, v238
	v_exp_f32_e32 v109, v223
	v_exp_f32_e32 v108, v239
	v_exp_f32_e32 v177, v224
	v_exp_f32_e32 v176, v240
	v_exp_f32_e32 v111, v225
	v_exp_f32_e32 v110, v241
	v_add_u32_e32 v242, 0x6800, v203
	v_add_u32_e32 v243, 0x7000, v203
	v_add_u32_e32 v244, 0x7800, v203
	v_add_u32_e32 v245, 0x8000, v203
	ds_read2_b64 v[210:213], v242 offset1:4
	ds_read2_b64 v[214:217], v243 offset0:32 offset1:36
	ds_read2_b64 v[218:221], v244 offset0:64 offset1:68
	ds_read2_b64 v[222:225], v245 offset0:96 offset1:100
	ds_read2_b64 v[226:229], v243 offset0:40 offset1:44
	ds_read2_b64 v[230:233], v242 offset0:8 offset1:12
	ds_read2_b64 v[234:237], v244 offset0:72 offset1:76
	ds_read2_b64 v[238:241], v245 offset0:104 offset1:108
	v_pk_add_f32 v[80:81], v[154:155], 0 op_sel_hi:[1,0]
	v_pk_add_f32 v[80:81], v[156:157], v[80:81]
	v_pk_add_f32 v[80:81], v[158:159], v[80:81]
	v_pk_add_f32 v[80:81], v[160:161], v[80:81]
	v_pk_add_f32 v[80:81], v[162:163], v[80:81]
	v_pk_mul_f32 v[102:103], v[66:67], v[178:179] op_sel_hi:[1,0]
	v_pk_add_f32 v[80:81], v[164:165], v[80:81]
	v_pk_mul_f32 v[100:101], v[64:65], v[178:179] op_sel_hi:[1,0]
	v_pk_add_f32 v[80:81], v[166:167], v[80:81]
	v_pk_mul_f32 v[64:65], v[76:77], v[178:179] op_sel_hi:[1,0]
	v_pk_add_f32 v[80:81], v[168:169], v[80:81]
	v_cvt_pk_bf16_f32 v76, v171, v105
	v_pk_mul_f32 v[98:99], v[70:71], v[178:179] op_sel_hi:[1,0]
	v_pk_add_f32 v[80:81], v[170:171], v[80:81]
	v_pk_mul_f32 v[96:97], v[68:69], v[178:179] op_sel_hi:[1,0]
	v_pk_add_f32 v[88:89], v[104:105], v[80:81]
	v_cvt_pk_bf16_f32 v68, v155, v157
	v_cvt_pk_bf16_f32 v69, v159, v161
	v_pk_mul_f32 v[84:85], v[52:53], v[90:91] op_sel_hi:[1,0]
	v_pk_add_f32 v[52:53], v[172:173], v[88:89]
	v_pk_mul_f32 v[82:83], v[50:51], v[90:91] op_sel_hi:[1,0]
	v_pk_add_f32 v[52:53], v[106:107], v[52:53]
	v_pk_mul_f32 v[80:81], v[48:49], v[90:91] op_sel_hi:[1,0]
	v_pk_add_f32 v[52:53], v[174:175], v[52:53]
	v_pk_mul_f32 v[86:87], v[54:55], v[90:91] op_sel_hi:[1,0]
	v_pk_add_f32 v[52:53], v[108:109], v[52:53]
	v_pk_mul_f32 v[58:59], v[58:59], v[90:91] op_sel_hi:[1,0]
	v_pk_add_f32 v[52:53], v[176:177], v[52:53]
	v_pk_mul_f32 v[56:57], v[56:57], v[90:91] op_sel_hi:[1,0]
	v_pk_mul_f32 v[50:51], v[62:63], v[90:91] op_sel_hi:[1,0]
	v_pk_mul_f32 v[48:49], v[60:61], v[90:91] op_sel_hi:[1,0]
	v_mov_b32_e32 v91, v178
	v_pk_add_f32 v[52:53], v[110:111], v[52:53]
	v_cvt_pk_bf16_f32 v60, v170, v104
	v_pk_fma_f32 v[120:121], v[120:121], v[90:91], v[52:53]
	v_cvt_pk_bf16_f32 v70, v163, v165
	v_cvt_pk_bf16_f32 v71, v167, v169
	v_cvt_pk_bf16_f32 v52, v154, v156
	v_cvt_pk_bf16_f32 v53, v158, v160
	v_cvt_pk_bf16_f32 v54, v162, v164
	v_cvt_pk_bf16_f32 v55, v166, v168
	v_cvt_pk_bf16_f32 v61, v172, v106
	s_waitcnt lgkmcnt(7)
; DEVI bf16x8 mk8(uint2 a, uint2 b) { union { uint4 u; bf16x8 v; } c; c.u = make_uint4(a.x, a.y, b.x, b.y); return c.v; }
; #define MFMA(a, b, c) __builtin_amdgcn_mfma_f32_16x16x32_bf16((a), (b), (c), 0, 0, 0)
; template <int DK, bool BIAS> ...
;     ...
; #pragma unroll
;       for (int k2 = 0; k2 < 2; ++k2)
; #pragma unroll
;         for (int et = 0; et < 4; ++et) {
;           const uint2 v0 = *(const uint2*)(Vtm + (buf * 64 + 16 * et + fr) * 72 + 32 * k2 + 4 * fq), v1 = *(const uint2*)(Vtm + (buf * 64 + 16 * et + fr) * 72 + 32 * k2 + 16 + 4 * fq);
;           const bf16x8 va = mk8(v0, v1);
; #pragma unroll
;           for (int qi = 0; qi < 2; ++qi) O[et][qi] = MFMA(va, pf[qi][k2], O[et][qi]);
;         }
	v_mfma_f32_16x16x32_bf16 v[92:95], v[210:213], v[68:71], v[100:103]
	v_pk_mul_f32 v[74:75], v[74:75], v[178:179] op_sel_hi:[1,0]
	v_pk_mul_f32 v[72:73], v[72:73], v[178:179] op_sel_hi:[1,0]
	v_mfma_f32_16x16x32_bf16 v[80:83], v[210:213], v[52:55], v[80:83]
	v_cvt_pk_bf16_f32 v77, v173, v107
	s_waitcnt lgkmcnt(6)
	v_mfma_f32_16x16x32_bf16 v[96:99], v[214:217], v[68:71], v[96:99]
	v_pk_mul_f32 v[66:67], v[78:79], v[178:179] op_sel_hi:[1,0]
	v_cvt_pk_bf16_f32 v78, v175, v109
	v_cvt_pk_bf16_f32 v79, v177, v111
	v_mfma_f32_16x16x32_bf16 v[84:87], v[214:217], v[52:55], v[84:87]
	v_cvt_pk_bf16_f32 v62, v174, v108
	v_cvt_pk_bf16_f32 v63, v176, v110
	s_waitcnt lgkmcnt(5)
	v_mfma_f32_16x16x32_bf16 v[72:75], v[218:221], v[68:71], v[72:75]
	v_mov_b32_e32 v208, v209
	v_mov_b32_e32 v154, v131
	v_mfma_f32_16x16x32_bf16 v[56:59], v[218:221], v[52:55], v[56:59]
	s_waitcnt lgkmcnt(4)
	v_mfma_f32_16x16x32_bf16 v[100:103], v[222:225], v[68:71], v[64:67]
	v_mfma_f32_16x16x32_bf16 v[88:91], v[222:225], v[52:55], v[48:51]
	s_nop 1
	s_waitcnt lgkmcnt(2)
	v_mfma_f32_16x16x32_bf16 v[64:67], v[230:233], v[76:79], v[92:95]
	v_mfma_f32_16x16x32_bf16 v[48:51], v[230:233], v[60:63], v[80:83]
	s_nop 2
	s_waitcnt lgkmcnt(1)
	v_mfma_f32_16x16x32_bf16 v[72:75], v[234:237], v[76:79], v[72:75]
	v_mfma_f32_16x16x32_bf16 v[56:59], v[234:237], v[60:63], v[56:59]
	v_mfma_f32_16x16x32_bf16 v[68:71], v[226:229], v[76:79], v[96:99]
	v_mfma_f32_16x16x32_bf16 v[52:55], v[226:229], v[60:63], v[84:87]
	s_waitcnt lgkmcnt(0)
	v_mfma_f32_16x16x32_bf16 v[76:79], v[238:241], v[76:79], v[100:103]
	v_mfma_f32_16x16x32_bf16 v[60:63], v[238:241], v[60:63], v[88:91]

; DEVI unsigned pk_bf16(float lo, float hi) { unsigned r; asm("v_cvt_pk_bf16_f32 %0, %1, %2" : "=v"(r) : "v"(lo), "v"(hi)); return r; }
; DEVI bf16x8 mk8(uint2 a, uint2 b) { union { uint4 u; bf16x8 v; } c; c.u = make_uint4(a.x, a.y, b.x, b.y); return c.v; }
; template <int DK, bool BIAS> ...
;     ...
;       for (int qi = 0; qi < 2; ++qi) {
;         float mx = -3e38f;
;         if (BIAS) {
; #pragma unroll
;           for (int kt = 0; kt < 4; ++kt) { const f32x4 nf = *(const f32x4*)(fkm + buf * 64 + 16 * kt + 4 * fq);
; #pragma unroll
;             for (int r = 0; r < 4; ++r) { const float t = fmaf(S[kt][qi][r], sc2, nf[r]); S[kt][qi][r] = t; mx = fmaxf(mx, t); } }
;         } else {
; #pragma unroll
;           for (int kt = 0; kt < 4; ++kt)
; #pragma unroll
;             for (int r = 0; r < 4; ++r) mx = fmaxf(mx, S[kt][qi][r]);
;           mx *= sc2;
;         }
;         mx = fmaxf(mx, __shfl_xor(mx, 16)); mx = fmaxf(mx, __shfl_xor(mx, 32));
;         const float mold = mrun[qi], mnew = fmaxf(mold, mx);
;         mrun[qi] = mnew;
;         float ps = 0.f;
; #pragma unroll
;         for (int kt = 0; kt < 4; ++kt)
; #pragma unroll
;           for (int r = 0; r < 4; ++r) { const float pv = BIAS ? __builtin_amdgcn_exp2f(S[kt][qi][r] - mnew) : __builtin_amdgcn_exp2f(fmaf(S[kt][qi][r], sc2, -mnew)); S[kt][qi][r] = pv; ps += pv; }
;         {
;           const float alpha = __builtin_amdgcn_exp2f(mold - mnew);
;           lrun[qi] *= alpha;
; #pragma unroll
;           for (int et = 0; et < 4; ++et) O[et][qi] *= alpha;
;         }
;         lrun[qi] += ps;
; #pragma unroll
;         for (int k2 = 0; k2 < 2; ++k2) { uint2 lo, hi; lo.x = pk_bf16(S[2 * k2][qi][0], S[2 * k2][qi][1]); lo.y = pk_bf16(S[2 * k2][qi][2], S[2 * k2][qi][3]);
;           hi.x = pk_bf16(S[2 * k2 + 1][qi][0], S[2 * k2 + 1][qi][1]); hi.y = pk_bf16(S[2 * k2 + 1][qi][2], S[2 * k2 + 1][qi][3]); pf[qi][k2] = mk8(lo, hi); }
;       }
; #pragma unroll
;       for (int k2 = 0; k2 < 2; ++k2)
; #pragma unroll
;         for (int et = 0; et < 4; ++et) {
;           const uint2 v0 = *(const uint2*)(Vtm + (buf * 64 + 16 * et + fr) * 72 + 32 * k2 + 4 * fq), v1 = *(const uint2*)(Vtm + (buf * 64 + 16 * et + fr) * 72 + 32 * k2 + 16 + 4 * fq);
;           const bf16x8 va = mk8(v0, v1);
; #pragma unroll
;           for (int qi = 0; qi < 2; ++qi) O[et][qi] = MFMA(va, pf[qi][k2], O[et][qi]);
;         }
.LBB0_1888:
	s_or_b64 exec, exec, s[18:19]
	s_mov_b32 s100, s34
	s_mov_b32 s101, s34
	v_lshlrev_b32_e32 v250, 2, v186
	v_max3_f32 v242, v96, s31, v97
	v_max3_f32 v243, v84, s31, v85
	v_max3_f32 v242, v242, v98, v99
	v_max3_f32 v243, v243, v86, v87
	v_max3_f32 v242, v242, v100, v101
	v_max3_f32 v243, v243, v88, v89
	v_max3_f32 v242, v242, v102, v103
	v_max3_f32 v243, v243, v90, v91
	v_max3_f32 v242, v242, v104, v105
	v_max3_f32 v243, v243, v80, v81
	v_max3_f32 v242, v242, v106, v107
	v_max3_f32 v243, v243, v82, v83
	v_max3_f32 v242, v242, v108, v109
	v_max3_f32 v243, v243, v92, v93
	v_max3_f32 v242, v242, v110, v111
	v_max3_f32 v243, v243, v94, v95
	v_mul_f32_e32 v242, 0x3e16c740, v242
	v_mul_f32_e32 v243, 0x3e16c740, v243
	v_mov_b32_e32 v244, v242
	v_mov_b32_e32 v245, v243
	s_nop 1
	v_permlane16_swap_b32_e32 v244, v242
	v_permlane16_swap_b32_e32 v245, v243
	v_max_f32_e32 v242, v242, v244
	v_max_f32_e32 v243, v243, v245
	v_mov_b32_e32 v244, v242
	v_mov_b32_e32 v245, v243
	s_nop 1
	v_permlane32_swap_b32_e32 v244, v242
	v_permlane32_swap_b32_e32 v245, v243
	v_max3_f32 v131, v154, v242, v244
	v_max3_f32 v209, v208, v243, v245
	v_sub_f32_e32 v242, v154, v131
	v_sub_f32_e32 v243, v208, v209
	v_sub_f32_e32 v246, 0, v131
	v_sub_f32_e32 v248, 0, v209
	v_pk_fma_f32 v[210:211], v[96:97], s[100:101], v[246:247] op_sel_hi:[1,1,0]
	v_pk_fma_f32 v[226:227], v[80:81], s[100:101], v[248:249] op_sel_hi:[1,1,0]
	v_pk_fma_f32 v[212:213], v[98:99], s[100:101], v[246:247] op_sel_hi:[1,1,0]
	v_pk_fma_f32 v[228:229], v[82:83], s[100:101], v[248:249] op_sel_hi:[1,1,0]
	v_pk_fma_f32 v[214:215], v[100:101], s[100:101], v[246:247] op_sel_hi:[1,1,0]
	v_pk_fma_f32 v[230:231], v[84:85], s[100:101], v[248:249] op_sel_hi:[1,1,0]
	v_pk_fma_f32 v[216:217], v[102:103], s[100:101], v[246:247] op_sel_hi:[1,1,0]
	v_pk_fma_f32 v[232:233], v[86:87], s[100:101], v[248:249] op_sel_hi:[1,1,0]
	v_pk_fma_f32 v[218:219], v[104:105], s[100:101], v[246:247] op_sel_hi:[1,1,0]
	v_pk_fma_f32 v[234:235], v[88:89], s[100:101], v[248:249] op_sel_hi:[1,1,0]
	v_pk_fma_f32 v[220:221], v[106:107], s[100:101], v[246:247] op_sel_hi:[1,1,0]
	v_pk_fma_f32 v[236:237], v[90:91], s[100:101], v[248:249] op_sel_hi:[1,1,0]
	v_pk_fma_f32 v[222:223], v[108:109], s[100:101], v[246:247] op_sel_hi:[1,1,0]
	v_pk_fma_f32 v[238:239], v[92:93], s[100:101], v[248:249] op_sel_hi:[1,1,0]
	v_pk_fma_f32 v[224:225], v[110:111], s[100:101], v[246:247] op_sel_hi:[1,1,0]
	v_pk_fma_f32 v[240:241], v[94:95], s[100:101], v[248:249] op_sel_hi:[1,1,0]
	v_exp_f32_e32 v178, v242
	v_exp_f32_e32 v90, v243
	v_exp_f32_e32 v163, v210
	v_exp_f32_e32 v162, v226
	v_exp_f32_e32 v165, v211
	v_exp_f32_e32 v164, v227
	v_exp_f32_e32 v167, v212
	v_exp_f32_e32 v166, v228
	v_exp_f32_e32 v169, v213
	v_exp_f32_e32 v168, v229
	v_exp_f32_e32 v155, v214
	v_exp_f32_e32 v170, v230
	v_exp_f32_e32 v157, v215
	v_exp_f32_e32 v104, v231
	v_exp_f32_e32 v159, v216
	v_exp_f32_e32 v172, v232
	v_exp_f32_e32 v161, v217
	v_exp_f32_e32 v106, v233
	v_exp_f32_e32 v171, v218
	v_exp_f32_e32 v154, v234
	v_exp_f32_e32 v105, v219
	v_exp_f32_e32 v156, v235
	v_exp_f32_e32 v173, v220
	v_exp_f32_e32 v158, v236
	v_exp_f32_e32 v107, v221
	v_exp_f32_e32 v160, v237
	v_exp_f32_e32 v175, v222
	v_exp_f32_e32 v174, v238
	v_exp_f32_e32 v109, v223
	v_exp_f32_e32 v108, v239
	v_exp_f32_e32 v177, v224
	v_exp_f32_e32 v176, v240
	v_exp_f32_e32 v111, v225
	v_exp_f32_e32 v110, v241
	v_add_u32_e32 v242, 0x6800, v206
	v_add_u32_e32 v243, 0x9000, v203
	v_add_u32_e32 v244, 0x9800, v203
	v_add_u32_e32 v245, 0xa000, v203
	ds_read2_b64 v[210:213], v242 offset1:4
	ds_read2_b64 v[214:217], v243 offset0:160 offset1:164
	ds_read2_b64 v[218:221], v244 offset0:192 offset1:196
	ds_read2_b64 v[222:225], v245 offset0:224 offset1:228
	ds_read2_b64 v[226:229], v243 offset0:168 offset1:172
	ds_read2_b64 v[230:233], v242 offset0:8 offset1:12
	ds_read2_b64 v[234:237], v244 offset0:200 offset1:204
	ds_read2_b64 v[238:241], v245 offset0:232 offset1:236
	v_pk_add_f32 v[80:81], v[154:155], 0 op_sel_hi:[1,0]
	v_pk_add_f32 v[80:81], v[156:157], v[80:81]
	v_pk_mul_f32 v[102:103], v[66:67], v[178:179] op_sel_hi:[1,0]
	v_pk_add_f32 v[80:81], v[158:159], v[80:81]
	v_pk_mul_f32 v[100:101], v[64:65], v[178:179] op_sel_hi:[1,0]
	v_pk_add_f32 v[80:81], v[160:161], v[80:81]
	v_pk_mul_f32 v[64:65], v[76:77], v[178:179] op_sel_hi:[1,0]
	v_pk_add_f32 v[80:81], v[162:163], v[80:81]
	v_cvt_pk_bf16_f32 v76, v171, v105
	v_pk_mul_f32 v[98:99], v[70:71], v[178:179] op_sel_hi:[1,0]
	v_pk_add_f32 v[80:81], v[164:165], v[80:81]
	v_pk_mul_f32 v[96:97], v[68:69], v[178:179] op_sel_hi:[1,0]
	v_pk_add_f32 v[88:89], v[166:167], v[80:81]
	v_cvt_pk_bf16_f32 v68, v155, v157
	v_cvt_pk_bf16_f32 v69, v159, v161
	v_cvt_pk_bf16_f32 v70, v163, v165
	v_cvt_pk_bf16_f32 v71, v167, v169
	v_pk_mul_f32 v[74:75], v[74:75], v[178:179] op_sel_hi:[1,0]
	v_pk_mul_f32 v[84:85], v[52:53], v[90:91] op_sel_hi:[1,0]
	v_pk_add_f32 v[52:53], v[168:169], v[88:89]
	v_pk_mul_f32 v[82:83], v[50:51], v[90:91] op_sel_hi:[1,0]
	v_pk_add_f32 v[52:53], v[170:171], v[52:53]
	v_pk_mul_f32 v[80:81], v[48:49], v[90:91] op_sel_hi:[1,0]
	v_pk_add_f32 v[52:53], v[104:105], v[52:53]
	v_pk_mul_f32 v[86:87], v[54:55], v[90:91] op_sel_hi:[1,0]
	v_pk_add_f32 v[52:53], v[172:173], v[52:53]
	v_pk_mul_f32 v[58:59], v[58:59], v[90:91] op_sel_hi:[1,0]
	v_pk_add_f32 v[52:53], v[106:107], v[52:53]
	v_pk_mul_f32 v[56:57], v[56:57], v[90:91] op_sel_hi:[1,0]
	v_pk_add_f32 v[52:53], v[174:175], v[52:53]
	v_pk_mul_f32 v[50:51], v[62:63], v[90:91] op_sel_hi:[1,0]
	v_pk_add_f32 v[52:53], v[108:109], v[52:53]
	v_pk_mul_f32 v[48:49], v[60:61], v[90:91] op_sel_hi:[1,0]
	v_pk_add_f32 v[52:53], v[176:177], v[52:53]
	v_mov_b32_e32 v91, v178
	v_pk_add_f32 v[52:53], v[110:111], v[52:53]
	v_cvt_pk_bf16_f32 v60, v170, v104
	v_pk_fma_f32 v[120:121], v[120:121], v[90:91], v[52:53]
	v_cvt_pk_bf16_f32 v52, v154, v156
	v_cvt_pk_bf16_f32 v53, v158, v160
	v_cvt_pk_bf16_f32 v54, v162, v164
	v_cvt_pk_bf16_f32 v55, v166, v168
	s_waitcnt lgkmcnt(7)
; DEVI bf16x8 mk8(uint2 a, uint2 b) { union { uint4 u; bf16x8 v; } c; c.u = make_uint4(a.x, a.y, b.x, b.y); return c.v; }
; #define MFMA(a, b, c) __builtin_amdgcn_mfma_f32_16x16x32_bf16((a), (b), (c), 0, 0, 0)
; template <int DK, bool BIAS> ...
;     ...
; #pragma unroll
;       for (int k2 = 0; k2 < 2; ++k2)
; #pragma unroll
;         for (int et = 0; et < 4; ++et) {
;           const uint2 v0 = *(const uint2*)(Vtm + (buf * 64 + 16 * et + fr) * 72 + 32 * k2 + 4 * fq), v1 = *(const uint2*)(Vtm + (buf * 64 + 16 * et + fr) * 72 + 32 * k2 + 16 + 4 * fq);
;           const bf16x8 va = mk8(v0, v1);
; #pragma unroll
;           for (int qi = 0; qi < 2; ++qi) O[et][qi] = MFMA(va, pf[qi][k2], O[et][qi]);
;         }
	v_mfma_f32_16x16x32_bf16 v[92:95], v[210:213], v[68:71], v[100:103]
	v_cvt_pk_bf16_f32 v61, v172, v106
	v_pk_mul_f32 v[72:73], v[72:73], v[178:179] op_sel_hi:[1,0]
	v_mfma_f32_16x16x32_bf16 v[80:83], v[210:213], v[52:55], v[80:83]
	v_cvt_pk_bf16_f32 v77, v173, v107
	s_waitcnt lgkmcnt(6)
	v_mfma_f32_16x16x32_bf16 v[96:99], v[214:217], v[68:71], v[96:99]
	v_pk_mul_f32 v[66:67], v[78:79], v[178:179] op_sel_hi:[1,0]
	v_cvt_pk_bf16_f32 v78, v175, v109
	v_cvt_pk_bf16_f32 v79, v177, v111
	v_mfma_f32_16x16x32_bf16 v[84:87], v[214:217], v[52:55], v[84:87]
	v_cvt_pk_bf16_f32 v62, v174, v108
	v_cvt_pk_bf16_f32 v63, v176, v110
	s_waitcnt lgkmcnt(5)
	v_mfma_f32_16x16x32_bf16 v[72:75], v[218:221], v[68:71], v[72:75]
	v_mov_b32_e32 v208, v209
	v_mov_b32_e32 v154, v131
	v_mfma_f32_16x16x32_bf16 v[56:59], v[218:221], v[52:55], v[56:59]
	s_waitcnt lgkmcnt(4)
	v_mfma_f32_16x16x32_bf16 v[100:103], v[222:225], v[68:71], v[64:67]
	v_mfma_f32_16x16x32_bf16 v[88:91], v[222:225], v[52:55], v[48:51]
	s_nop 1
	s_waitcnt lgkmcnt(2)
	v_mfma_f32_16x16x32_bf16 v[64:67], v[230:233], v[76:79], v[92:95]
	v_mfma_f32_16x16x32_bf16 v[48:51], v[230:233], v[60:63], v[80:83]
	s_nop 2
	s_waitcnt lgkmcnt(1)
	v_mfma_f32_16x16x32_bf16 v[72:75], v[234:237], v[76:79], v[72:75]
	v_mfma_f32_16x16x32_bf16 v[56:59], v[234:237], v[60:63], v[56:59]
	v_mfma_f32_16x16x32_bf16 v[68:71], v[226:229], v[76:79], v[96:99]
	v_mfma_f32_16x16x32_bf16 v[52:55], v[226:229], v[60:63], v[84:87]
	s_waitcnt lgkmcnt(0)
	v_mfma_f32_16x16x32_bf16 v[76:79], v[238:241], v[76:79], v[100:103]
	v_mfma_f32_16x16x32_bf16 v[60:63], v[238:241], v[60:63], v[88:91]
